# weight-transpose split point moved from 0x3c80 to 0x3800 (more of the share in P4, whose non-scan side has slack)
# speedup vs baseline: 1.0004x; 1.0004x over previous
; __device__ __forceinline__ int lane_id() { int l; asm volatile("v_mbcnt_lo_u32_b32 %0, -1, 0\n\tv_mbcnt_hi_u32_b32 %0, -1, %0" : "=v"(l)); return l; }
; #define LAS __attribute__((address_space(3)))
; __device__ __forceinline__ void phase_wconv_rest(const Params& p, LAS unsigned char* lds, int gw, int NGW) {
;     const int lane = lane_id(), wave = p.wave_id;
;     LAS float* scr = (LAS float*)(lds + 16384 + wave * 16384);
;     constexpr int I_A = (WA / 64) * (D_MODEL / 32), I_O = (D_MODEL / 64) * (D_MODEL / 32), I_1 = (D_MODEL / 64) * (FFN / 32), I_2 = (FFN / 64) * (D_MODEL / 32);
;     constexpr int NITEMS = 2 * I_A + I_O + 2 * I_1 + I_2;
;     unsigned char* ws = p.ws;
;     const float* sh2 = (const float*)(ws + WS_MOD) + 3 * D_MODEL; float* b2 = (float*)(ws + WS_BIAS2);
;     for (int it = gw; it < NITEMS; it += NGW) {
;         int r = it;
;         if (r < I_A) { transpose_item<false, false>(p.w_a, WA, D_MODEL, (bf16*)(ws + WS_WAT), 0, scr, r, lane); continue; } r -= I_A;
;         if (r < I_A) { transpose_item<false, false>(p.w_b, WA, D_MODEL, (bf16*)(ws + WS_WBT), 0, scr, r, lane); continue; } r -= I_A;
;         if (r < I_O) { transpose_item<false, false>(p.w_o, D_MODEL, D_MODEL, (bf16*)(ws + WS_WOT), 0, scr, r, lane); continue; } r -= I_O;
;         if (r < I_1) { transpose_item<false, true>(p.w1, D_MODEL, FFN, (bf16*)(ws + WS_W13T), 0, scr, r, lane, sh2, b2); continue; } r -= I_1;
;         if (r < I_1) { transpose_item<false, true>(p.w3, D_MODEL, FFN, (bf16*)(ws + WS_W13T), 128, scr, r, lane, sh2, b2); continue; } r -= I_1;
;         transpose_item<false, false>(p.w2, FFN, D_MODEL, (bf16*)(ws + WS_W2T), 0, scr, r, lane);
;     }
; }
; __global__ void __launch_bounds__(NTHREADS, 2) mega_fwd(Params p_in) {
;     ...
;       const int nfree = nb - CTX_UNITS;
;       if (nfree >= 64) { if (bx >= CTX_UNITS) phase_wconv_rest(p, lds, (bx - CTX_UNITS) * 8 + wave_id, nfree * 8); }
;       else phase_wconv_rest(p, lds, bx * 8 + wave_id, nb * 8); }
.LBB0_240:
	s_cmpk_lt_i32 s2, 0x50
	s_cbranch_scc1 .LBB0_268
	s_lshl_b32 s4, s2, 3
	s_add_i32 s4, s4, s3
	s_add_i32 s20, s4, 0xfffffd80
	s_movk_i32 s98, 0x51ff
	s_cmpk_lg_i32 s33, 0x100
	s_cselect_b32 s98, s98, 0x37ff
	s_cmp_gt_i32 s20, s98
	v_mbcnt_lo_u32_b32 v0, -1, 0
	v_mbcnt_hi_u32_b32 v0, -1, v0
	s_cbranch_scc1 .LBB0_268
	s_add_i32 s21, s46, 0xfffffd80
	s_waitcnt lgkmcnt(0)
	s_add_u32 s6, s22, 0x106000
	s_addc_u32 s7, s23, 0
	s_add_u32 s16, s22, 0x18000
	s_addc_u32 s17, s23, 0
	s_lshl_b32 s3, s3, 14
	v_ashrrev_i32_e32 v34, 5, v0
	v_lshlrev_b32_e32 v1, 2, v0
	s_movk_i32 s4, 0x84
	s_add_i32 s3, s3, 0
	v_and_b32_e32 v22, 0x7c, v1
	v_mul_lo_u32 v1, v34, s4
	v_add3_u32 v26, s3, v22, v1
	v_lshlrev_b32_e32 v1, 3, v0
	v_and_b32_e32 v1, 56, v1
	v_ashrrev_i32_e32 v35, 3, v0
	v_lshlrev_b32_e32 v12, 1, v1
	v_mov_b32_e32 v13, 0
	v_mul_u32_u24_e32 v4, 0x84, v1
	v_lshl_add_u64 v[10:11], s[22:23], 0, v[12:13]
	v_lshlrev_b32_e32 v1, 2, v35
	s_mov_b64 s[22:23], 0x142000
	v_add3_u32 v27, s3, v4, v1
	v_lshl_add_u64 v[4:5], v[10:11], 0, s[22:23]
	s_mov_b64 s[22:23], 0x4b42000
	v_lshl_add_u64 v[6:7], v[10:11], 0, s[22:23]
	s_mov_b64 s[22:23], 0x4742000
	s_mov_b64 s[4:5], 0x2d42000
	v_ashrrev_i32_e32 v1, 31, v0
	v_lshl_add_u64 v[8:9], v[10:11], 0, s[22:23]
	s_mov_b64 s[22:23], 0x4342000
	v_mov_b32_e32 v23, v13
	s_mov_b32 s19, 0
	v_lshl_add_u64 v[2:3], v[10:11], 0, s[4:5]
	v_add_u32_e32 v36, 8, v35
	v_add_u32_e32 v37, 16, v35
	v_add_u32_e32 v38, 24, v35
	v_cmp_gt_i32_e64 s[4:5], 32, v0
	v_lshl_add_u64 v[10:11], v[10:11], 0, s[22:23]
	v_lshl_add_u64 v[12:13], s[42:43], 0, v[22:23]
	v_lshl_add_u64 v[14:15], s[40:41], 0, v[22:23]
	v_lshl_add_u64 v[16:17], s[14:15], 0, v[22:23]
	v_lshl_add_u64 v[18:19], s[12:13], 0, v[22:23]
	v_lshl_add_u64 v[20:21], s[10:11], 0, v[22:23]
	v_lshl_add_u64 v[22:23], s[8:9], 0, v[22:23]
	v_lshl_add_u64 v[24:25], v[0:1], 2, s[16:17]
	s_lshl_b32 s3, s20, 5
	s_lshl_b32 s12, s21, 5
	s_mov_b32 s13, 0xc000
	s_mov_b32 s14, 0x18000
	s_mov_b32 s15, 0x24000
	s_movk_i32 s22, 0x2c00
	s_movk_i32 s23, 0x5800
	v_add_u32_e32 v39, 0x4000, v26
	v_add_u32_e32 v40, 0x4400, v26
	v_add_u32_e32 v41, 0x4800, v26
	v_add_u32_e32 v42, 0x4c00, v26
	v_add_u32_e32 v43, 0x5000, v26
	v_add_u32_e32 v44, 0x5400, v26
	v_add_u32_e32 v45, 0x5800, v26
	v_add_u32_e32 v46, 0x5c00, v26
	v_add_u32_e32 v47, 0x4000, v27
	s_branch .LBB0_244

; __device__ __forceinline__ int lane_id() { int l; asm volatile("v_mbcnt_lo_u32_b32 %0, -1, 0\n\tv_mbcnt_hi_u32_b32 %0, -1, %0" : "=v"(l)); return l; }
; #define LOAD_P() Params p; { const __attribute__((address_space(4))) Params* q_ = (const __attribute__((address_space(4))) Params*)__builtin_amdgcn_kernarg_segment_ptr(); asm volatile("" : "+s"(q_)); \
;     p = *q_; p.wave_id = wave_id; } unsigned char* ws = p.ws; (void)ws
; __device__ __forceinline__ void phase_wconv_rest(const Params& p, LAS unsigned char* lds, int gw, int NGW) {
;     ...
;     for (int it = gw; it < NITEMS; it += NGW) {
;         int r = it;
;         if (r < I_A) { transpose_item<false, false>(p.w_a, WA, D_MODEL, (bf16*)(ws + WS_WAT), 0, scr, r, lane); continue; } r -= I_A;
;         if (r < I_A) { transpose_item<false, false>(p.w_b, WA, D_MODEL, (bf16*)(ws + WS_WBT), 0, scr, r, lane); continue; } r -= I_A;
;         if (r < I_O) { transpose_item<false, false>(p.w_o, D_MODEL, D_MODEL, (bf16*)(ws + WS_WOT), 0, scr, r, lane); continue; } r -= I_O;
;         if (r < I_1) { transpose_item<false, true>(p.w1, D_MODEL, FFN, (bf16*)(ws + WS_W13T), 0, scr, r, lane, sh2, b2); continue; } r -= I_1;
;         if (r < I_1) { transpose_item<false, true>(p.w3, D_MODEL, FFN, (bf16*)(ws + WS_W13T), 128, scr, r, lane, sh2, b2); continue; } r -= I_1;
;         transpose_item<false, false>(p.w2, FFN, D_MODEL, (bf16*)(ws + WS_W2T), 0, scr, r, lane);
; __global__ void __launch_bounds__(NTHREADS, 2) mega_fwd(Params p_in) {
;     ...
;     { LOAD_P();
;       if (bx < 2 * BATCH * NHEAD) {
;         if (wave_id == 0 && lane_id() == 0) { unsigned* pc = (unsigned*)(ws + WS_PREPCTR); while (__hip_atomic_load(pc, __ATOMIC_RELAXED, __HIP_MEMORY_SCOPE_AGENT) < (unsigned)nb) __builtin_amdgcn_s_sleep(2); }
;         asm volatile("" ::: "memory"); __syncthreads();
;         hgrn_scan(p, lds, bx); }
;       __syncthreads();
;       phase_attn(p, lds); }
.Lw2_first:
	s_cmpk_lg_i32 s33, 0x100
	s_cbranch_scc1 .LBB0_436
	s_waitcnt lgkmcnt(0)
	v_writelane_b32 v250, s3, 40
	v_writelane_b32 v250, s12, 41
	v_writelane_b32 v250, s18, 42
	v_writelane_b32 v250, s19, 43
	v_writelane_b32 v250, s20, 44
	v_writelane_b32 v250, s21, 45
	v_writelane_b32 v250, s22, 46
	v_writelane_b32 v250, s23, 47
	v_writelane_b32 v250, s24, 48
	v_writelane_b32 v250, s25, 49
	v_writelane_b32 v250, s26, 50
	v_writelane_b32 v250, s27, 51
	s_lshr_b32 s3, s76, 6
	s_load_dwordx8 s[8:15], s[0:1], 0x70
	s_load_dwordx2 s[40:41], s[0:1], 0x90
	s_load_dwordx2 s[42:43], s[0:1], 0xa8
	s_load_dwordx2 s[22:23], s[0:1], 0xb8
	s_waitcnt vmcnt(0) lgkmcnt(0)
	s_barrier
	s_sub_i32 s4, s2, 64
	s_mul_hi_u32 s96, s4, 0x55555556
	s_mul_i32 s97, s96, 3
	s_sub_i32 s97, s4, s97
	s_cmp_eq_u32 s97, 2
	s_cbranch_scc1 .Lw2_classb
	s_lshl_b32 s4, s96, 1
	s_add_i32 s4, s4, s97
	s_lshl_b32 s4, s4, 3
	s_add_i32 s4, s4, s3
	s_add_i32 s20, s4, 0x3800
	s_movk_i32 s21, 0x400
	s_movk_i32 s97, 0x44ff
	s_branch .Lw2_classdone
.Lw2_classb:
	s_lshl_b32 s4, s96, 3
	s_add_i32 s4, s4, s3
	s_add_i32 s20, s4, 0x4500
	s_movk_i32 s21, 0x200
	s_movk_i32 s97, 0x51ff
